# MoBA packed chunk loop: common path falls through (single-tile init and tile-A rescale out of line), on top of the dilated-loop version
# speedup vs baseline: 1.0188x; 1.0124x over previous
.LBB0_1927:
	v_max_f32_e32 v2, v112, v113
	v_max3_f32 v2, v2, v114, v115
	v_max3_f32 v2, v2, v116, v117
	v_max3_f32 v2, v2, v118, v119
	v_max3_f32 v2, v2, v120, v121
	v_max3_f32 v2, v2, v122, v123
	v_max3_f32 v2, v2, v124, v125
	v_max3_f32 v2, v2, v126, v127
	v_mov_b32_e32 v3, v2
	s_nop 1
	v_permlane32_swap_b32_e32 v2, v3
	v_max_f32_e32 v2, v2, v3
	v_cmp_lt_f32_e32 vcc, s88, v2
	s_cbranch_vccnz .Lmb_rescA

.Lmb_one:
	v_mov_b32_e32 v109, v96
	v_mov_b32_e32 v110, v96
	v_mov_b32_e32 v111, v96
	s_branch .LBB0_1927
.Lmb_rescA:
	v_max_f32_e32 v2, v2, v2
	v_max_f32_e32 v2, 0, v2
	v_exp_f32_e64 v4, -v2
	v_add_f32_e32 v1, v1, v2
	v_pk_add_f32 v[112:113], v[112:113], v[2:3] op_sel_hi:[1,0] neg_lo:[0,1] neg_hi:[0,1]
	v_pk_add_f32 v[114:115], v[114:115], v[2:3] op_sel_hi:[1,0] neg_lo:[0,1] neg_hi:[0,1]
	v_pk_add_f32 v[116:117], v[116:117], v[2:3] op_sel_hi:[1,0] neg_lo:[0,1] neg_hi:[0,1]
	v_pk_add_f32 v[118:119], v[118:119], v[2:3] op_sel_hi:[1,0] neg_lo:[0,1] neg_hi:[0,1]
	v_pk_add_f32 v[120:121], v[120:121], v[2:3] op_sel_hi:[1,0] neg_lo:[0,1] neg_hi:[0,1]
	v_pk_add_f32 v[122:123], v[122:123], v[2:3] op_sel_hi:[1,0] neg_lo:[0,1] neg_hi:[0,1]
	v_pk_add_f32 v[124:125], v[124:125], v[2:3] op_sel_hi:[1,0] neg_lo:[0,1] neg_hi:[0,1]
	v_pk_add_f32 v[126:127], v[126:127], v[2:3] op_sel_hi:[1,0] neg_lo:[0,1] neg_hi:[0,1]
	v_mul_f32_e32 v240, v240, v4
	v_pk_mul_f32 v[62:63], v[62:63], v[4:5] op_sel_hi:[1,0]
	v_pk_mul_f32 v[60:61], v[60:61], v[4:5] op_sel_hi:[1,0]
	v_pk_mul_f32 v[58:59], v[58:59], v[4:5] op_sel_hi:[1,0]
	v_pk_mul_f32 v[56:57], v[56:57], v[4:5] op_sel_hi:[1,0]
	v_pk_mul_f32 v[54:55], v[54:55], v[4:5] op_sel_hi:[1,0]
	v_pk_mul_f32 v[52:53], v[52:53], v[4:5] op_sel_hi:[1,0]
	v_pk_mul_f32 v[50:51], v[50:51], v[4:5] op_sel_hi:[1,0]
	v_pk_mul_f32 v[48:49], v[48:49], v[4:5] op_sel_hi:[1,0]
	v_pk_mul_f32 v[78:79], v[78:79], v[4:5] op_sel_hi:[1,0]
	v_pk_mul_f32 v[76:77], v[76:77], v[4:5] op_sel_hi:[1,0]
	v_pk_mul_f32 v[74:75], v[74:75], v[4:5] op_sel_hi:[1,0]
	v_pk_mul_f32 v[72:73], v[72:73], v[4:5] op_sel_hi:[1,0]
	v_pk_mul_f32 v[70:71], v[70:71], v[4:5] op_sel_hi:[1,0]
	v_pk_mul_f32 v[68:69], v[68:69], v[4:5] op_sel_hi:[1,0]
	v_pk_mul_f32 v[66:67], v[66:67], v[4:5] op_sel_hi:[1,0]
	v_pk_mul_f32 v[64:65], v[64:65], v[4:5] op_sel_hi:[1,0]
	s_branch .LBB0_1929
